# rope-table lookups at attention Q-tile load (2 sites) and post-projection rope: all 16/8 table loads issued up front with re-materialised addresses instead of 8/4 serialized round trips
# speedup vs baseline: 1.0177x; 1.0004x over previous
.LBB0_301:
	s_lshr_b32 s1, s1, 6
	s_and_b32 s27, s0, 63
	v_mov_b32_e32 v10, s27
	v_mov_b32_e32 v11, s1
	v_cndmask_b32_e64 v10, v10, v11, s[10:11]
	v_lshl_or_b32 v16, v10, 8, v122
	global_load_dwordx2 v[34:35], v16, s[22:23]
	v_or_b32_e32 v36, 16, v16
	global_load_dwordx2 v[38:39], v36, s[22:23]
	v_or_b32_e32 v36, 32, v16
	global_load_dwordx2 v[40:41], v36, s[22:23]
	v_or_b32_e32 v42, 48, v16
	global_load_dwordx2 v[36:37], v42, s[22:23]
	v_or_b32_e32 v44, 64, v16
	global_load_dwordx2 v[42:43], v44, s[22:23]
	v_or_b32_e32 v46, 0x50, v16
	global_load_dwordx2 v[44:45], v46, s[22:23]
	v_or_b32_e32 v48, 0x60, v16
	global_load_dwordx2 v[46:47], v48, s[22:23]
	v_or_b32_e32 v50, 0x70, v16
	global_load_dwordx2 v[48:49], v50, s[22:23]
	v_or_b32_e32 v12, 16, v16
	s_nop 0
	v_mov_b32_dpp v4, v18 quad_perm:[2,3,0,1] row_mask:0xf bank_mask:0xf bound_ctrl:1
	s_nop 0
	v_mov_b32_dpp v5, v19 quad_perm:[2,3,0,1] row_mask:0xf bank_mask:0xf bound_ctrl:1
	v_mov_b32_dpp v6, v20 quad_perm:[2,3,0,1] row_mask:0xf bank_mask:0xf bound_ctrl:1
	v_mov_b32_dpp v7, v21 quad_perm:[2,3,0,1] row_mask:0xf bank_mask:0xf bound_ctrl:1
	v_mov_b32_dpp v8, v22 quad_perm:[2,3,0,1] row_mask:0xf bank_mask:0xf bound_ctrl:1
	v_mov_b32_dpp v9, v23 quad_perm:[2,3,0,1] row_mask:0xf bank_mask:0xf bound_ctrl:1
	v_mov_b32_dpp v2, v24 quad_perm:[2,3,0,1] row_mask:0xf bank_mask:0xf bound_ctrl:1
	v_mov_b32_dpp v3, v25 quad_perm:[2,3,0,1] row_mask:0xf bank_mask:0xf bound_ctrl:1
	s_or_b64 s[14:15], s[14:15], exec
	s_waitcnt vmcnt(8)
	s_waitcnt vmcnt(7)
	v_mov_b32_e32 v14, v35
	s_waitcnt vmcnt(6)
	v_mov_b32_e32 v15, v39
	v_pk_mul_f32 v[4:5], v[14:15], v[4:5]
	v_mov_b32_e32 v35, v38
	v_cndmask_b32_e64 v5, v5, -v5, s[12:13]
	v_cndmask_b32_e64 v4, v4, -v4, s[12:13]
	v_pk_fma_f32 v[18:19], v[18:19], v[34:35], v[4:5]
	v_or_b32_e32 v4, 32, v16
	v_or_b32_e32 v34, 48, v16
	s_nop 0
	s_nop 0
	s_nop 0
	s_waitcnt vmcnt(5)
	v_mov_b32_e32 v38, v41
	s_waitcnt vmcnt(4)
	v_mov_b32_e32 v39, v37
	v_pk_mul_f32 v[6:7], v[38:39], v[6:7]
	v_mov_b32_e32 v41, v36
	v_cndmask_b32_e64 v7, v7, -v7, s[12:13]
	v_cndmask_b32_e64 v6, v6, -v6, s[12:13]
	v_pk_fma_f32 v[20:21], v[20:21], v[40:41], v[6:7]
	v_or_b32_e32 v40, 64, v16
	v_or_b32_e32 v6, 0x50, v16
	s_nop 0
	s_nop 0
	s_nop 0
	s_waitcnt vmcnt(3)
	v_mov_b32_e32 v36, v43
	s_waitcnt vmcnt(2)
	v_mov_b32_e32 v37, v45
	v_pk_mul_f32 v[8:9], v[36:37], v[8:9]
	v_mov_b32_e32 v43, v44
	v_cndmask_b32_e64 v45, v9, -v9, s[12:13]
	v_cndmask_b32_e64 v44, v8, -v8, s[12:13]
	v_pk_fma_f32 v[22:23], v[22:23], v[42:43], v[44:45]
	v_or_b32_e32 v42, 0x60, v16
	v_or_b32_e32 v44, 0x70, v16
	s_nop 0
	s_nop 0
	s_nop 0
	s_waitcnt vmcnt(1)
	v_mov_b32_e32 v8, v47
	s_waitcnt vmcnt(0)
	v_mov_b32_e32 v9, v49
	v_pk_mul_f32 v[2:3], v[8:9], v[2:3]
	v_mov_b32_e32 v47, v48
	v_cndmask_b32_e64 v3, v3, -v3, s[12:13]
	v_cndmask_b32_e64 v2, v2, -v2, s[12:13]
	v_pk_fma_f32 v[24:25], v[26:27], v[46:47], v[2:3]

.LBB0_483:
	s_lshl_b32 s33, s30, 10
	s_addk_i32 s33, 0x2000
	s_or_b32 s36, s33, s35
	s_lshl_b32 s34, s30, 8
	s_and_b64 s[30:31], s[12:13], exec
	s_cselect_b32 s31, s36, s34
	s_and_b32 s30, s21, 7
	s_mul_i32 s36, s31, 0xc00
	s_mul_hi_u32 s21, s31, 0xc00
	s_add_u32 s36, s19, s36
	s_addc_u32 s21, s24, s21
	s_mul_i32 s37, s30, 0x180
	s_add_u32 s38, s36, s37
	s_addc_u32 s39, s21, 0
	v_readfirstlane_b32 s21, v168
	s_ashr_i32 s21, s21, 6
	s_lshl_b32 s36, s21, 5
	v_or_b32_e32 v0, s36, v172
	v_mov_b64_e32 v[2:3], s[38:39]
	s_movk_i32 s37, 0xc00
	v_mad_i64_i32 v[2:3], s[38:39], v0, s37, v[2:3]
	v_lshlrev_b32_e32 v0, 1, v174
	v_lshl_add_u64 v[14:15], v[2:3], 0, v[0:1]
	global_load_dwordx4 v[126:129], v[14:15], off
	global_load_dwordx4 v[122:125], v[14:15], off offset:32
	global_load_dwordx4 v[118:121], v[14:15], off offset:64
	global_load_dwordx4 v[114:117], v[14:15], off offset:96
	global_load_dwordx4 v[110:113], v[14:15], off offset:128
	global_load_dwordx4 v[106:109], v[14:15], off offset:160
	global_load_dwordx4 v[102:105], v[14:15], off offset:192
	global_load_dwordx4 v[98:101], v[14:15], off offset:224
	global_load_dwordx4 v[2:5], v[14:15], off offset:256
	global_load_dwordx4 v[6:9], v[14:15], off offset:288
	global_load_dwordx4 v[10:13], v[14:15], off offset:320
	s_nop 0
	global_load_dwordx4 v[14:17], v[14:15], off offset:352
	s_cmp_lg_u64 s[14:15], 0
	s_cbranch_scc0 .LBB0_493
	v_or_b32_e32 v40, s35, v172
	v_add_u32_e32 v40, s36, v40
	v_ashrrev_i32_e32 v58, 1, v40
	s_movk_i32 s98, 0xffe0
	v_and_or_b32 v60, v58, s98, v171
	v_ashrrev_i32_e32 v61, 31, v60
	v_lshl_add_u64 v[58:59], v[60:61], 3, s[14:15]
	global_load_dwordx2 v[42:43], v[58:59], off
	v_or_b32_e32 v40, s35, v172
	v_add_u32_e32 v40, s36, v40
	v_ashrrev_i32_e32 v58, 1, v40
	s_movk_i32 s98, 0xffe0
	v_and_or_b32 v60, v58, s98, v171
	v_or_b32_e32 v58, 2, v60
	v_ashrrev_i32_e32 v59, 31, v58
	v_lshl_add_u64 v[58:59], v[58:59], 3, s[14:15]
	global_load_dwordx2 v[44:45], v[58:59], off
	v_or_b32_e32 v40, s35, v172
	v_add_u32_e32 v40, s36, v40
	v_ashrrev_i32_e32 v58, 1, v40
	s_movk_i32 s98, 0xffe0
	v_and_or_b32 v60, v58, s98, v171
	v_or_b32_e32 v64, 4, v60
	v_ashrrev_i32_e32 v65, 31, v64
	v_lshl_add_u64 v[64:65], v[64:65], 3, s[14:15]
	global_load_dwordx2 v[46:47], v[64:65], off
	v_or_b32_e32 v40, s35, v172
	v_add_u32_e32 v40, s36, v40
	v_ashrrev_i32_e32 v58, 1, v40
	s_movk_i32 s98, 0xffe0
	v_and_or_b32 v60, v58, s98, v171
	v_or_b32_e32 v66, 6, v60
	v_ashrrev_i32_e32 v67, 31, v66
	v_lshl_add_u64 v[66:67], v[66:67], 3, s[14:15]
	global_load_dwordx2 v[48:49], v[66:67], off
	v_or_b32_e32 v40, s35, v172
	v_add_u32_e32 v40, s36, v40
	v_ashrrev_i32_e32 v58, 1, v40
	s_movk_i32 s98, 0xffe0
	v_and_or_b32 v60, v58, s98, v171
	v_or_b32_e32 v68, 8, v60
	v_ashrrev_i32_e32 v69, 31, v68
	v_lshl_add_u64 v[68:69], v[68:69], 3, s[14:15]
	global_load_dwordx2 v[50:51], v[68:69], off
	v_or_b32_e32 v40, s35, v172
	v_add_u32_e32 v40, s36, v40
	v_ashrrev_i32_e32 v58, 1, v40
	s_movk_i32 s98, 0xffe0
	v_and_or_b32 v60, v58, s98, v171
	v_or_b32_e32 v70, 10, v60
	v_ashrrev_i32_e32 v71, 31, v70
	v_lshl_add_u64 v[70:71], v[70:71], 3, s[14:15]
	global_load_dwordx2 v[52:53], v[70:71], off
	v_or_b32_e32 v40, s35, v172
	v_add_u32_e32 v40, s36, v40
	v_ashrrev_i32_e32 v58, 1, v40
	s_movk_i32 s98, 0xffe0
	v_and_or_b32 v60, v58, s98, v171
	v_or_b32_e32 v72, 12, v60
	v_ashrrev_i32_e32 v73, 31, v72
	v_lshl_add_u64 v[72:73], v[72:73], 3, s[14:15]
	global_load_dwordx2 v[54:55], v[72:73], off
	v_or_b32_e32 v40, s35, v172
	v_add_u32_e32 v40, s36, v40
	v_ashrrev_i32_e32 v58, 1, v40
	s_movk_i32 s98, 0xffe0
	v_and_or_b32 v60, v58, s98, v171
	v_or_b32_e32 v60, 14, v60
	v_ashrrev_i32_e32 v61, 31, v60
	v_lshl_add_u64 v[60:61], v[60:61], 3, s[14:15]
	global_load_dwordx2 v[56:57], v[60:61], off
	v_or_b32_e32 v40, s35, v172
	v_add_u32_e32 v40, s36, v40
	v_lshlrev_b32_e32 v40, 5, v40
	s_movk_i32 s98, 0x7e0
	v_and_or_b32 v40, v40, s98, v171
	v_lshlrev_b32_e32 v40, 3, v40
	global_load_dwordx2 v[58:59], v40, s[14:15]
	v_or_b32_e32 v40, s35, v172
	v_add_u32_e32 v40, s36, v40
	v_lshlrev_b32_e32 v40, 5, v40
	s_movk_i32 s98, 0x7e0
	v_and_or_b32 v40, v40, s98, v171
	v_lshlrev_b32_e32 v40, 3, v40
	global_load_dwordx2 v[60:61], v40, s[14:15] offset:16
	v_or_b32_e32 v40, s35, v172
	v_add_u32_e32 v40, s36, v40
	v_lshlrev_b32_e32 v40, 5, v40
	s_movk_i32 s98, 0x7e0
	v_and_or_b32 v40, v40, s98, v171
	v_lshlrev_b32_e32 v40, 3, v40
	global_load_dwordx2 v[62:63], v40, s[14:15] offset:32
	v_or_b32_e32 v40, s35, v172
	v_add_u32_e32 v40, s36, v40
	v_lshlrev_b32_e32 v40, 5, v40
	s_movk_i32 s98, 0x7e0
	v_and_or_b32 v40, v40, s98, v171
	v_lshlrev_b32_e32 v40, 3, v40
	global_load_dwordx2 v[64:65], v40, s[14:15] offset:48
	v_or_b32_e32 v40, s35, v172
	v_add_u32_e32 v40, s36, v40
	v_lshlrev_b32_e32 v40, 5, v40
	s_movk_i32 s98, 0x7e0
	v_and_or_b32 v40, v40, s98, v171
	v_lshlrev_b32_e32 v40, 3, v40
	global_load_dwordx2 v[66:67], v40, s[14:15] offset:64
	v_or_b32_e32 v40, s35, v172
	v_add_u32_e32 v40, s36, v40
	v_lshlrev_b32_e32 v40, 5, v40
	s_movk_i32 s98, 0x7e0
	v_and_or_b32 v40, v40, s98, v171
	v_lshlrev_b32_e32 v40, 3, v40
	global_load_dwordx2 v[68:69], v40, s[14:15] offset:80
	v_or_b32_e32 v40, s35, v172
	v_add_u32_e32 v40, s36, v40
	v_lshlrev_b32_e32 v40, 5, v40
	s_movk_i32 s98, 0x7e0
	v_and_or_b32 v40, v40, s98, v171
	v_lshlrev_b32_e32 v40, 3, v40
	global_load_dwordx2 v[70:71], v40, s[14:15] offset:96
	v_or_b32_e32 v40, s35, v172
	v_add_u32_e32 v40, s36, v40
	v_lshlrev_b32_e32 v40, 5, v40
	s_movk_i32 s98, 0x7e0
	v_and_or_b32 v40, v40, s98, v171
	v_lshlrev_b32_e32 v40, 3, v40
	global_load_dwordx2 v[72:73], v40, s[14:15] offset:112
	v_or_b32_e32 v0, s35, v172
	v_add_u32_e32 v0, s36, v0
	v_ashrrev_i32_e32 v18, 1, v0
	s_movk_i32 s35, 0xffe0
	v_and_or_b32 v20, v18, s35, v171
	v_ashrrev_i32_e32 v21, 31, v20
	v_lshl_add_u64 v[18:19], v[20:21], 3, s[14:15]
	s_nop 0
	v_or_b32_e32 v18, 2, v20
	v_ashrrev_i32_e32 v19, 31, v18
	v_lshl_add_u64 v[18:19], v[18:19], 3, s[14:15]
	s_nop 0
	s_waitcnt vmcnt(18)
	v_lshlrev_b32_e32 v26, 16, v6
	v_and_b32_e32 v27, 0xffff0000, v6
	v_lshlrev_b32_e32 v24, 16, v2
	v_and_b32_e32 v25, 0xffff0000, v2
	v_lshlrev_b32_e32 v30, 16, v7
	v_and_b32_e32 v31, 0xffff0000, v7
	v_lshlrev_b32_e32 v34, 16, v8
	v_and_b32_e32 v35, 0xffff0000, v8
	v_lshlrev_b32_e32 v0, 5, v0
	s_movk_i32 s35, 0x7e0
	v_and_or_b32 v0, v0, s35, v171
	v_lshlrev_b32_e32 v0, 3, v0
	s_waitcnt vmcnt(16)
	s_waitcnt vmcnt(15)
	v_mov_b32_e32 v28, v43
	s_waitcnt vmcnt(14)
	v_mov_b32_e32 v29, v45
	v_mov_b32_e32 v43, v44
	v_pk_mul_f32 v[44:45], v[42:43], v[26:27]
	v_pk_mul_f32 v[26:27], v[28:29], v[26:27]
	v_pk_fma_f32 v[44:45], v[28:29], v[24:25], v[44:45]
	v_pk_fma_f32 v[42:43], v[42:43], v[24:25], v[26:27] neg_lo:[0,0,1] neg_hi:[0,0,1]
	v_or_b32_e32 v24, 4, v20
	v_or_b32_e32 v26, 6, v20
	v_ashrrev_i32_e32 v25, 31, v24
	v_ashrrev_i32_e32 v27, 31, v26
	v_lshl_add_u64 v[24:25], v[24:25], 3, s[14:15]
	v_lshl_add_u64 v[26:27], v[26:27], 3, s[14:15]
	s_nop 0
	v_lshlrev_b32_e32 v28, 16, v3
	s_nop 0
	v_and_b32_e32 v29, 0xffff0000, v3
	v_cvt_pk_bf16_f32 v130, v44, v45
	v_cvt_pk_bf16_f32 v134, v42, v43
	v_lshlrev_b32_e32 v42, 16, v10
	v_and_b32_e32 v43, 0xffff0000, v10
	s_waitcnt vmcnt(13)
	v_mov_b32_e32 v32, v47
	s_waitcnt vmcnt(12)
	v_mov_b32_e32 v33, v49
	v_mov_b32_e32 v47, v48
	v_pk_mul_f32 v[48:49], v[46:47], v[30:31]
	v_pk_mul_f32 v[30:31], v[32:33], v[30:31]
	v_pk_fma_f32 v[48:49], v[32:33], v[28:29], v[48:49]
	v_pk_fma_f32 v[46:47], v[46:47], v[28:29], v[30:31] neg_lo:[0,0,1] neg_hi:[0,0,1]
	v_or_b32_e32 v28, 8, v20
	v_or_b32_e32 v30, 10, v20
	v_ashrrev_i32_e32 v29, 31, v28
	v_ashrrev_i32_e32 v31, 31, v30
	v_lshl_add_u64 v[28:29], v[28:29], 3, s[14:15]
	v_lshl_add_u64 v[30:31], v[30:31], 3, s[14:15]
	s_nop 0
	v_lshlrev_b32_e32 v32, 16, v4
	s_nop 0
	v_and_b32_e32 v33, 0xffff0000, v4
	v_cvt_pk_bf16_f32 v135, v46, v47
	v_cvt_pk_bf16_f32 v131, v48, v49
	v_lshlrev_b32_e32 v46, 16, v14
	v_and_b32_e32 v47, 0xffff0000, v14
	s_waitcnt vmcnt(11)
	v_mov_b32_e32 v36, v51
	s_waitcnt vmcnt(10)
	v_mov_b32_e32 v37, v53
	v_mov_b32_e32 v51, v52
	v_pk_mul_f32 v[52:53], v[50:51], v[34:35]
	v_pk_mul_f32 v[34:35], v[36:37], v[34:35]
	v_pk_fma_f32 v[52:53], v[36:37], v[32:33], v[52:53]
	v_pk_fma_f32 v[50:51], v[50:51], v[32:33], v[34:35] neg_lo:[0,0,1] neg_hi:[0,0,1]
	v_or_b32_e32 v32, 12, v20
	v_or_b32_e32 v20, 14, v20
	v_ashrrev_i32_e32 v33, 31, v32
	v_ashrrev_i32_e32 v21, 31, v20
	v_lshl_add_u64 v[32:33], v[32:33], 3, s[14:15]
	v_lshl_add_u64 v[20:21], v[20:21], 3, s[14:15]
	s_nop 0
	v_lshlrev_b32_e32 v36, 16, v9
	s_nop 0
	v_and_b32_e32 v37, 0xffff0000, v9
	v_lshlrev_b32_e32 v34, 16, v5
	v_and_b32_e32 v35, 0xffff0000, v5
	v_cvt_pk_bf16_f32 v136, v50, v51
	v_cvt_pk_bf16_f32 v132, v52, v53
	v_lshlrev_b32_e32 v50, 16, v15
	v_and_b32_e32 v51, 0xffff0000, v15
	s_waitcnt vmcnt(9)
	v_mov_b32_e32 v38, v55
	s_waitcnt vmcnt(8)
	v_mov_b32_e32 v55, v56
	v_mov_b32_e32 v39, v57
	v_pk_mul_f32 v[56:57], v[54:55], v[36:37]
	v_pk_mul_f32 v[36:37], v[38:39], v[36:37]
	v_pk_fma_f32 v[56:57], v[38:39], v[34:35], v[56:57]
	v_pk_fma_f32 v[54:55], v[54:55], v[34:35], v[36:37] neg_lo:[0,0,1] neg_hi:[0,0,1]
	v_cvt_pk_bf16_f32 v133, v56, v57
	s_nop 0
	s_nop 0
	v_cvt_pk_bf16_f32 v137, v54, v55
	v_lshlrev_b32_e32 v54, 16, v16
	v_and_b32_e32 v55, 0xffff0000, v16
	v_lshlrev_b32_e32 v36, 16, v17
	v_and_b32_e32 v37, 0xffff0000, v17
	s_waitcnt vmcnt(7)
	v_mov_b32_e32 v48, v59
	s_waitcnt vmcnt(6)
	v_mov_b32_e32 v49, v61
	v_mov_b32_e32 v59, v60
	v_pk_mul_f32 v[60:61], v[58:59], v[46:47]
	v_pk_mul_f32 v[46:47], v[48:49], v[46:47]
	v_pk_fma_f32 v[60:61], v[48:49], v[42:43], v[60:61]
	v_pk_fma_f32 v[58:59], v[58:59], v[42:43], v[46:47] neg_lo:[0,0,1] neg_hi:[0,0,1]
	s_nop 0
	s_nop 0
	v_lshlrev_b32_e32 v48, 16, v11
	v_and_b32_e32 v49, 0xffff0000, v11
	v_cvt_pk_bf16_f32 v142, v58, v59
	v_cvt_pk_bf16_f32 v138, v60, v61
	s_waitcnt vmcnt(5)
	v_mov_b32_e32 v52, v63
	s_waitcnt vmcnt(4)
	v_mov_b32_e32 v53, v65
	v_mov_b32_e32 v63, v64
	v_pk_mul_f32 v[64:65], v[62:63], v[50:51]
	v_pk_mul_f32 v[50:51], v[52:53], v[50:51]
	v_pk_fma_f32 v[64:65], v[52:53], v[48:49], v[64:65]
	v_pk_fma_f32 v[62:63], v[62:63], v[48:49], v[50:51] neg_lo:[0,0,1] neg_hi:[0,0,1]
	s_nop 0
	s_nop 0
	v_lshlrev_b32_e32 v52, 16, v12
	v_and_b32_e32 v53, 0xffff0000, v12
	v_cvt_pk_bf16_f32 v143, v62, v63
	v_cvt_pk_bf16_f32 v139, v64, v65
	s_waitcnt vmcnt(3)
	v_mov_b32_e32 v34, v67
	s_waitcnt vmcnt(2)
	v_mov_b32_e32 v35, v69
	v_mov_b32_e32 v67, v68
	v_pk_mul_f32 v[68:69], v[66:67], v[54:55]
	v_pk_mul_f32 v[54:55], v[34:35], v[54:55]
	v_pk_fma_f32 v[68:69], v[34:35], v[52:53], v[68:69]
	v_pk_fma_f32 v[66:67], v[66:67], v[52:53], v[54:55] neg_lo:[0,0,1] neg_hi:[0,0,1]
	s_nop 0
	s_nop 0
	v_lshlrev_b32_e32 v34, 16, v13
	v_and_b32_e32 v35, 0xffff0000, v13
	v_cvt_pk_bf16_f32 v144, v66, v67
	v_cvt_pk_bf16_f32 v140, v68, v69
	s_waitcnt vmcnt(1)
	v_mov_b32_e32 v38, v71
	s_waitcnt vmcnt(0)
	v_mov_b32_e32 v39, v73
	v_mov_b32_e32 v71, v72
	v_pk_mul_f32 v[72:73], v[70:71], v[36:37]
	v_pk_mul_f32 v[36:37], v[38:39], v[36:37]
	v_pk_fma_f32 v[72:73], v[38:39], v[34:35], v[72:73]
	v_pk_fma_f32 v[70:71], v[70:71], v[34:35], v[36:37] neg_lo:[0,0,1] neg_hi:[0,0,1]
	v_cvt_pk_bf16_f32 v141, v72, v73
	v_cvt_pk_bf16_f32 v145, v70, v71
	s_cbranch_execnz .LBB0_486

.LBB0_778:
	s_lshl_b64 s[6:7], s[6:7], 1
	s_add_u32 s36, s28, s6
	v_readfirstlane_b32 s33, v164
	s_addc_u32 s37, s29, s7
	s_ashr_i32 s33, s33, 6
	s_lshl_b32 s40, s33, 5
	v_or_b32_e32 v0, s40, v179
	v_mov_b64_e32 v[2:3], s[36:37]
	s_movk_i32 s36, 0x2400
	v_mad_i64_i32 v[2:3], s[36:37], v0, s36, v[2:3]
	v_lshlrev_b32_e32 v0, 1, v168
	v_lshl_add_u64 v[14:15], v[2:3], 0, v[0:1]
	global_load_dwordx4 v[2:5], v[14:15], off
	global_load_dwordx4 v[6:9], v[14:15], off offset:32
	global_load_dwordx4 v[10:13], v[14:15], off offset:64
	s_nop 0
	global_load_dwordx4 v[14:17], v[14:15], off offset:96
	s_and_b64 vcc, exec, s[0:1]
	s_mov_b64 s[36:37], -1
	s_cbranch_vccz .LBB0_780
	v_add_u32_e32 v40, s40, v142
	v_ashrrev_i32_e32 v58, 1, v40
	s_movk_i32 s98, 0xffe0
	v_and_or_b32 v60, v58, s98, v212
	v_ashrrev_i32_e32 v61, 31, v60
	v_lshl_add_u64 v[58:59], v[60:61], 3, s[22:23]
	global_load_dwordx2 v[42:43], v[58:59], off
	v_add_u32_e32 v40, s40, v142
	v_ashrrev_i32_e32 v58, 1, v40
	s_movk_i32 s98, 0xffe0
	v_and_or_b32 v60, v58, s98, v212
	v_or_b32_e32 v58, 2, v60
	v_ashrrev_i32_e32 v59, 31, v58
	v_lshl_add_u64 v[58:59], v[58:59], 3, s[22:23]
	global_load_dwordx2 v[44:45], v[58:59], off
	v_add_u32_e32 v40, s40, v142
	v_ashrrev_i32_e32 v58, 1, v40
	s_movk_i32 s98, 0xffe0
	v_and_or_b32 v60, v58, s98, v212
	v_or_b32_e32 v64, 4, v60
	v_ashrrev_i32_e32 v65, 31, v64
	v_lshl_add_u64 v[64:65], v[64:65], 3, s[22:23]
	global_load_dwordx2 v[46:47], v[64:65], off
	v_add_u32_e32 v40, s40, v142
	v_ashrrev_i32_e32 v58, 1, v40
	s_movk_i32 s98, 0xffe0
	v_and_or_b32 v60, v58, s98, v212
	v_or_b32_e32 v66, 6, v60
	v_ashrrev_i32_e32 v67, 31, v66
	v_lshl_add_u64 v[66:67], v[66:67], 3, s[22:23]
	global_load_dwordx2 v[48:49], v[66:67], off
	v_add_u32_e32 v40, s40, v142
	v_ashrrev_i32_e32 v58, 1, v40
	s_movk_i32 s98, 0xffe0
	v_and_or_b32 v60, v58, s98, v212
	v_or_b32_e32 v68, 8, v60
	v_ashrrev_i32_e32 v69, 31, v68
	v_lshl_add_u64 v[68:69], v[68:69], 3, s[22:23]
	global_load_dwordx2 v[50:51], v[68:69], off
	v_add_u32_e32 v40, s40, v142
	v_ashrrev_i32_e32 v58, 1, v40
	s_movk_i32 s98, 0xffe0
	v_and_or_b32 v60, v58, s98, v212
	v_or_b32_e32 v70, 10, v60
	v_ashrrev_i32_e32 v71, 31, v70
	v_lshl_add_u64 v[70:71], v[70:71], 3, s[22:23]
	global_load_dwordx2 v[52:53], v[70:71], off
	v_add_u32_e32 v40, s40, v142
	v_ashrrev_i32_e32 v58, 1, v40
	s_movk_i32 s98, 0xffe0
	v_and_or_b32 v60, v58, s98, v212
	v_or_b32_e32 v72, 12, v60
	v_ashrrev_i32_e32 v73, 31, v72
	v_lshl_add_u64 v[72:73], v[72:73], 3, s[22:23]
	global_load_dwordx2 v[54:55], v[72:73], off
	v_add_u32_e32 v40, s40, v142
	v_ashrrev_i32_e32 v58, 1, v40
	s_movk_i32 s98, 0xffe0
	v_and_or_b32 v60, v58, s98, v212
	v_or_b32_e32 v60, 14, v60
	v_ashrrev_i32_e32 v61, 31, v60
	v_lshl_add_u64 v[60:61], v[60:61], 3, s[22:23]
	global_load_dwordx2 v[56:57], v[60:61], off
	v_add_u32_e32 v40, s40, v142
	v_lshlrev_b32_e32 v40, 5, v40
	s_movk_i32 s98, 0x7e0
	v_and_or_b32 v40, v40, s98, v212
	v_lshlrev_b32_e32 v40, 3, v40
	global_load_dwordx2 v[58:59], v40, s[22:23]
	v_add_u32_e32 v40, s40, v142
	v_lshlrev_b32_e32 v40, 5, v40
	s_movk_i32 s98, 0x7e0
	v_and_or_b32 v40, v40, s98, v212
	v_lshlrev_b32_e32 v40, 3, v40
	global_load_dwordx2 v[60:61], v40, s[22:23] offset:16
	v_add_u32_e32 v40, s40, v142
	v_lshlrev_b32_e32 v40, 5, v40
	s_movk_i32 s98, 0x7e0
	v_and_or_b32 v40, v40, s98, v212
	v_lshlrev_b32_e32 v40, 3, v40
	global_load_dwordx2 v[62:63], v40, s[22:23] offset:32
	v_add_u32_e32 v40, s40, v142
	v_lshlrev_b32_e32 v40, 5, v40
	s_movk_i32 s98, 0x7e0
	v_and_or_b32 v40, v40, s98, v212
	v_lshlrev_b32_e32 v40, 3, v40
	global_load_dwordx2 v[64:65], v40, s[22:23] offset:48
	v_add_u32_e32 v40, s40, v142
	v_lshlrev_b32_e32 v40, 5, v40
	s_movk_i32 s98, 0x7e0
	v_and_or_b32 v40, v40, s98, v212
	v_lshlrev_b32_e32 v40, 3, v40
	global_load_dwordx2 v[66:67], v40, s[22:23] offset:64
	v_add_u32_e32 v40, s40, v142
	v_lshlrev_b32_e32 v40, 5, v40
	s_movk_i32 s98, 0x7e0
	v_and_or_b32 v40, v40, s98, v212
	v_lshlrev_b32_e32 v40, 3, v40
	global_load_dwordx2 v[68:69], v40, s[22:23] offset:80
	v_add_u32_e32 v40, s40, v142
	v_lshlrev_b32_e32 v40, 5, v40
	s_movk_i32 s98, 0x7e0
	v_and_or_b32 v40, v40, s98, v212
	v_lshlrev_b32_e32 v40, 3, v40
	global_load_dwordx2 v[70:71], v40, s[22:23] offset:96
	v_add_u32_e32 v40, s40, v142
	v_lshlrev_b32_e32 v40, 5, v40
	s_movk_i32 s98, 0x7e0
	v_and_or_b32 v40, v40, s98, v212
	v_lshlrev_b32_e32 v40, 3, v40
	global_load_dwordx2 v[72:73], v40, s[22:23] offset:112
	v_add_u32_e32 v0, s40, v142
	v_ashrrev_i32_e32 v18, 1, v0
	s_movk_i32 s36, 0xffe0
	v_and_or_b32 v20, v18, s36, v212
	v_ashrrev_i32_e32 v21, 31, v20
	v_lshl_add_u64 v[18:19], v[20:21], 3, s[22:23]
	s_nop 0
	v_or_b32_e32 v18, 2, v20
	v_ashrrev_i32_e32 v19, 31, v18
	v_lshl_add_u64 v[18:19], v[18:19], 3, s[22:23]
	s_nop 0
	s_waitcnt vmcnt(18)
	v_lshlrev_b32_e32 v26, 16, v6
	v_and_b32_e32 v27, 0xffff0000, v6
	v_lshlrev_b32_e32 v24, 16, v2
	v_and_b32_e32 v25, 0xffff0000, v2
	v_lshlrev_b32_e32 v30, 16, v7
	v_and_b32_e32 v31, 0xffff0000, v7
	v_lshlrev_b32_e32 v34, 16, v8
	v_and_b32_e32 v35, 0xffff0000, v8
	v_lshlrev_b32_e32 v0, 5, v0
	s_movk_i32 s36, 0x7e0
	v_and_or_b32 v0, v0, s36, v212
	v_lshlrev_b32_e32 v0, 3, v0
	s_mov_b64 s[36:37], 0
	s_waitcnt vmcnt(16)
	s_waitcnt vmcnt(15)
	v_mov_b32_e32 v28, v43
	s_waitcnt vmcnt(14)
	v_mov_b32_e32 v29, v45
	v_mov_b32_e32 v43, v44
	v_pk_mul_f32 v[44:45], v[42:43], v[26:27]
	v_pk_mul_f32 v[26:27], v[28:29], v[26:27]
	v_pk_fma_f32 v[44:45], v[28:29], v[24:25], v[44:45]
	v_pk_fma_f32 v[42:43], v[42:43], v[24:25], v[26:27] neg_lo:[0,0,1] neg_hi:[0,0,1]
	v_or_b32_e32 v24, 4, v20
	v_or_b32_e32 v26, 6, v20
	v_ashrrev_i32_e32 v25, 31, v24
	v_ashrrev_i32_e32 v27, 31, v26
	v_lshl_add_u64 v[24:25], v[24:25], 3, s[22:23]
	v_lshl_add_u64 v[26:27], v[26:27], 3, s[22:23]
	s_nop 0
	v_lshlrev_b32_e32 v28, 16, v3
	s_nop 0
	v_and_b32_e32 v29, 0xffff0000, v3
	v_cvt_pk_bf16_f32 v112, v44, v45
	v_cvt_pk_bf16_f32 v116, v42, v43
	v_lshlrev_b32_e32 v42, 16, v10
	v_and_b32_e32 v43, 0xffff0000, v10
	s_waitcnt vmcnt(13)
	v_mov_b32_e32 v32, v47
	s_waitcnt vmcnt(12)
	v_mov_b32_e32 v33, v49
	v_mov_b32_e32 v47, v48
	v_pk_mul_f32 v[48:49], v[46:47], v[30:31]
	v_pk_mul_f32 v[30:31], v[32:33], v[30:31]
	v_pk_fma_f32 v[48:49], v[32:33], v[28:29], v[48:49]
	v_pk_fma_f32 v[46:47], v[46:47], v[28:29], v[30:31] neg_lo:[0,0,1] neg_hi:[0,0,1]
	v_or_b32_e32 v28, 8, v20
	v_or_b32_e32 v30, 10, v20
	v_ashrrev_i32_e32 v29, 31, v28
	v_ashrrev_i32_e32 v31, 31, v30
	v_lshl_add_u64 v[28:29], v[28:29], 3, s[22:23]
	v_lshl_add_u64 v[30:31], v[30:31], 3, s[22:23]
	s_nop 0
	v_lshlrev_b32_e32 v32, 16, v4
	s_nop 0
	v_and_b32_e32 v33, 0xffff0000, v4
	v_cvt_pk_bf16_f32 v117, v46, v47
	v_cvt_pk_bf16_f32 v113, v48, v49
	v_lshlrev_b32_e32 v46, 16, v14
	v_and_b32_e32 v47, 0xffff0000, v14
	s_waitcnt vmcnt(11)
	v_mov_b32_e32 v36, v51
	s_waitcnt vmcnt(10)
	v_mov_b32_e32 v37, v53
	v_mov_b32_e32 v51, v52
	v_pk_mul_f32 v[52:53], v[50:51], v[34:35]
	v_pk_mul_f32 v[34:35], v[36:37], v[34:35]
	v_pk_fma_f32 v[52:53], v[36:37], v[32:33], v[52:53]
	v_pk_fma_f32 v[50:51], v[50:51], v[32:33], v[34:35] neg_lo:[0,0,1] neg_hi:[0,0,1]
	v_or_b32_e32 v32, 12, v20
	v_or_b32_e32 v20, 14, v20
	v_ashrrev_i32_e32 v33, 31, v32
	v_ashrrev_i32_e32 v21, 31, v20
	v_lshl_add_u64 v[32:33], v[32:33], 3, s[22:23]
	v_lshl_add_u64 v[20:21], v[20:21], 3, s[22:23]
	s_nop 0
	v_lshlrev_b32_e32 v36, 16, v9
	s_nop 0
	v_and_b32_e32 v37, 0xffff0000, v9
	v_lshlrev_b32_e32 v34, 16, v5
	v_and_b32_e32 v35, 0xffff0000, v5
	v_cvt_pk_bf16_f32 v118, v50, v51
	v_cvt_pk_bf16_f32 v114, v52, v53
	v_lshlrev_b32_e32 v50, 16, v15
	v_and_b32_e32 v51, 0xffff0000, v15
	s_waitcnt vmcnt(9)
	v_mov_b32_e32 v38, v55
	s_waitcnt vmcnt(8)
	v_mov_b32_e32 v55, v56
	v_mov_b32_e32 v39, v57
	v_pk_mul_f32 v[56:57], v[54:55], v[36:37]
	v_pk_mul_f32 v[36:37], v[38:39], v[36:37]
	v_pk_fma_f32 v[56:57], v[38:39], v[34:35], v[56:57]
	v_pk_fma_f32 v[54:55], v[54:55], v[34:35], v[36:37] neg_lo:[0,0,1] neg_hi:[0,0,1]
	v_cvt_pk_bf16_f32 v115, v56, v57
	s_nop 0
	s_nop 0
	v_cvt_pk_bf16_f32 v119, v54, v55
	v_lshlrev_b32_e32 v54, 16, v16
	v_and_b32_e32 v55, 0xffff0000, v16
	v_lshlrev_b32_e32 v36, 16, v17
	v_and_b32_e32 v37, 0xffff0000, v17
	s_waitcnt vmcnt(7)
	v_mov_b32_e32 v48, v59
	s_waitcnt vmcnt(6)
	v_mov_b32_e32 v49, v61
	v_mov_b32_e32 v59, v60
	v_pk_mul_f32 v[60:61], v[58:59], v[46:47]
	v_pk_mul_f32 v[46:47], v[48:49], v[46:47]
	v_pk_fma_f32 v[60:61], v[48:49], v[42:43], v[60:61]
	v_pk_fma_f32 v[58:59], v[58:59], v[42:43], v[46:47] neg_lo:[0,0,1] neg_hi:[0,0,1]
	s_nop 0
	s_nop 0
	v_lshlrev_b32_e32 v48, 16, v11
	v_and_b32_e32 v49, 0xffff0000, v11
	v_cvt_pk_bf16_f32 v124, v58, v59
	v_cvt_pk_bf16_f32 v120, v60, v61
	s_waitcnt vmcnt(5)
	v_mov_b32_e32 v52, v63
	s_waitcnt vmcnt(4)
	v_mov_b32_e32 v53, v65
	v_mov_b32_e32 v63, v64
	v_pk_mul_f32 v[64:65], v[62:63], v[50:51]
	v_pk_mul_f32 v[50:51], v[52:53], v[50:51]
	v_pk_fma_f32 v[64:65], v[52:53], v[48:49], v[64:65]
	v_pk_fma_f32 v[62:63], v[62:63], v[48:49], v[50:51] neg_lo:[0,0,1] neg_hi:[0,0,1]
	s_nop 0
	s_nop 0
	v_lshlrev_b32_e32 v52, 16, v12
	v_and_b32_e32 v53, 0xffff0000, v12
	v_cvt_pk_bf16_f32 v125, v62, v63
	v_cvt_pk_bf16_f32 v121, v64, v65
	s_waitcnt vmcnt(3)
	v_mov_b32_e32 v34, v67
	s_waitcnt vmcnt(2)
	v_mov_b32_e32 v35, v69
	v_mov_b32_e32 v67, v68
	v_pk_mul_f32 v[68:69], v[66:67], v[54:55]
	v_pk_mul_f32 v[54:55], v[34:35], v[54:55]
	v_pk_fma_f32 v[68:69], v[34:35], v[52:53], v[68:69]
	v_pk_fma_f32 v[66:67], v[66:67], v[52:53], v[54:55] neg_lo:[0,0,1] neg_hi:[0,0,1]
	s_nop 0
	s_nop 0
	v_lshlrev_b32_e32 v34, 16, v13
	v_and_b32_e32 v35, 0xffff0000, v13
	v_cvt_pk_bf16_f32 v126, v66, v67
	v_cvt_pk_bf16_f32 v122, v68, v69
	s_waitcnt vmcnt(1)
	v_mov_b32_e32 v38, v71
	s_waitcnt vmcnt(0)
	v_mov_b32_e32 v39, v73
	v_mov_b32_e32 v71, v72
	v_pk_mul_f32 v[72:73], v[70:71], v[36:37]
	v_pk_mul_f32 v[36:37], v[38:39], v[36:37]
	v_pk_fma_f32 v[72:73], v[38:39], v[34:35], v[72:73]
	v_pk_fma_f32 v[70:71], v[70:71], v[34:35], v[36:37] neg_lo:[0,0,1] neg_hi:[0,0,1]
	v_cvt_pk_bf16_f32 v123, v72, v73
	v_cvt_pk_bf16_f32 v127, v70, v71
